# bias tables shifted by the last-bucket bias (softmax shift invariance); far key tiles start QK from C=0 and skip the table reads in units A and C
# speedup vs baseline: 1.0011x; 1.0011x over previous
; __global__ void __launch_bounds__(512, 2) fwd_kernel(Args a) {
;     ...
;         for (int idx = gtid; idx < 12 * TABN; idx += NTHR) { const int h = idx / TABN, dist = (TABN - 1 - idx % TABN) - TABOFF; float v = NEGV;
;             if (dist >= 0) { int bucket = dist;
;                 if (dist >= 16) { const float nf = (float)dist; const float t = logf(nf / 16.0f) / 4.852030263919617f * 16.0f; int lg = 16 + (int)t; bucket = lg < 31 ? lg : 31; }
;                 const float bias = a.in[2][bucket * 12 + h];
;                 if (h >= 4 && h < 8) { const int mult = (dist <= 128 ? 1 : 0) + (((dist & 3) == 0 && dist <= 512) ? 1 : 0) + (((dist & 15) == 0 && dist <= 2048) ? 1 : 0);
;                     if (mult > 0) v = (bias + logf((float)mult)) * LOG2E; }
;                 else v = bias * LOG2E; }
;             tabs[idx] = v; }
.LBB0_189:
	s_or_b64 exec, exec, s[0:1]
	v_mad_u64_u32 v[10:11], s[0:1], v9, 12, v[4:5]
	v_ashrrev_i32_e32 v11, 31, v10
	v_lshl_add_u64 v[10:11], v[10:11], 2, s[56:57]
	v_add_u32_e32 v78, 0x174, v4
	v_mov_b32_e32 v79, 0
	v_lshl_add_u64 v[78:79], v[78:79], 2, s[56:57]
	global_load_dword v80, v[78:79], off
	global_load_dword v4, v[10:11], off
	v_add_u32_e32 v9, 0xffffbc00, v2
	v_cmp_lt_u32_e32 vcc, s37, v9
	s_and_saveexec_b64 s[0:1], vcc
	s_xor_b64 s[0:1], exec, s[0:1]
	s_cbranch_execz .LBB0_191
	s_waitcnt vmcnt(0)
	v_sub_f32_e32 v4, v4, v80
	v_mul_f32_e32 v9, 0x3fb8aa3b, v4

; __device__ __forceinline__ int crowc(int r) { return (r & 3) + 8 * (r >> 2); }
; template <int D, int DV, bool TAB, bool BITS, int KT> ...
;     ...
;             if (D == 64) {
;                 bf16x8 ka[4], kb[4];
;                 if (TAB) {
; #pragma unroll
;                     for (int r = 0; r < 16; ++r) p0[r] = tabL[tj + crowc(r)]; }
; #pragma unroll
;                 for (int kk = 0; kk < 4; ++kk) ka[kk] = *(const bf16x8*)(Kl + r32 * KP + (kk * 16 + 8 * hi) * 2);
;                 if (TAB) {
; #pragma unroll
;                     for (int r = 0; r < 16; ++r) p1[r] = tabL[tj + 32 + crowc(r)]; }
; #pragma unroll
;                 for (int kk = 0; kk < 4; ++kk) kb[kk] = *(const bf16x8*)(Kl + (32 + r32) * KP + (kk * 16 + 8 * hi) * 2);
;                 __builtin_amdgcn_sched_barrier(0);
; #pragma unroll
;                 for (int r = 0; r < 16; ++r) { if (TAB) p0[r] -= mhat; else p0[r] = nm; if (BITS) { if (!((w0 >> crowc(r)) & 1u)) p0[r] = NEGV; } }
;                 __builtin_amdgcn_sched_barrier(0);
; #pragma unroll
;                 for (int kk = 0; kk < 4; ++kk) p0 = __builtin_amdgcn_mfma_f32_32x32x16_bf16(ka[kk], qf[kk], p0, 0, 0, 0);
; #pragma unroll
;                 for (int r = 0; r < 16; ++r) { if (TAB) p1[r] -= mhat; else p1[r] = nm; if (BITS) { if (!((w1 >> crowc(r)) & 1u)) p1[r] = NEGV; } }
;                 __builtin_amdgcn_sched_barrier(0);
; #pragma unroll
;                 for (int kk = 0; kk < 4; ++kk) p1 = __builtin_amdgcn_mfma_f32_32x32x16_bf16(kb[kk], qf[kk], p1, 0, 0, 0);
;                 __builtin_amdgcn_sched_barrier(0);
.Lfar_qk_a1s0:
	ds_read_b128 v[66:69], v183
	ds_read_b128 v[70:73], v183 offset:32
	ds_read_b128 v[208:211], v183 offset:64
	ds_read_b128 v[212:215], v183 offset:96
	s_waitcnt lgkmcnt(2)
	v_mfma_f32_32x32x16_bf16 v[82:97], v[66:69], v[134:137], 0
	v_mfma_f32_32x32x16_bf16 v[82:97], v[70:73], v[130:133], v[82:97]
	ds_read_b128 v[192:195], v183 offset:4608
	ds_read_b128 v[196:199], v183 offset:4640
	ds_read_b128 v[200:203], v183 offset:4672
	ds_read_b128 v[204:207], v183 offset:4704
	s_waitcnt lgkmcnt(4)
	v_mfma_f32_32x32x16_bf16 v[82:97], v[208:211], v[126:129], v[82:97]
	v_mfma_f32_32x32x16_bf16 v[82:97], v[212:215], v[122:125], v[82:97]
	s_waitcnt lgkmcnt(0)
	v_mfma_f32_32x32x16_bf16 v[66:81], v[192:195], v[134:137], 0
	v_mfma_f32_32x32x16_bf16 v[66:81], v[196:199], v[130:133], v[66:81]
	v_mfma_f32_32x32x16_bf16 v[66:81], v[200:203], v[126:129], v[66:81]
	v_mfma_f32_32x32x16_bf16 v[66:81], v[204:207], v[122:125], v[66:81]
	s_branch .Ljoin_qk_a1s0

; __device__ __forceinline__ int crowc(int r) { return (r & 3) + 8 * (r >> 2); }
; template <int D, int DV, bool TAB, bool BITS, int KT> ...
;     ...
;             if (D == 64) {
;                 bf16x8 ka[4], kb[4];
;                 if (TAB) {
; #pragma unroll
;                     for (int r = 0; r < 16; ++r) p0[r] = tabL[tj + crowc(r)]; }
; #pragma unroll
;                 for (int kk = 0; kk < 4; ++kk) ka[kk] = *(const bf16x8*)(Kl + r32 * KP + (kk * 16 + 8 * hi) * 2);
;                 if (TAB) {
; #pragma unroll
;                     for (int r = 0; r < 16; ++r) p1[r] = tabL[tj + 32 + crowc(r)]; }
; #pragma unroll
;                 for (int kk = 0; kk < 4; ++kk) kb[kk] = *(const bf16x8*)(Kl + (32 + r32) * KP + (kk * 16 + 8 * hi) * 2);
;                 __builtin_amdgcn_sched_barrier(0);
; #pragma unroll
;                 for (int r = 0; r < 16; ++r) { if (TAB) p0[r] -= mhat; else p0[r] = nm; if (BITS) { if (!((w0 >> crowc(r)) & 1u)) p0[r] = NEGV; } }
;                 __builtin_amdgcn_sched_barrier(0);
; #pragma unroll
;                 for (int kk = 0; kk < 4; ++kk) p0 = __builtin_amdgcn_mfma_f32_32x32x16_bf16(ka[kk], qf[kk], p0, 0, 0, 0);
; #pragma unroll
;                 for (int r = 0; r < 16; ++r) { if (TAB) p1[r] -= mhat; else p1[r] = nm; if (BITS) { if (!((w1 >> crowc(r)) & 1u)) p1[r] = NEGV; } }
;                 __builtin_amdgcn_sched_barrier(0);
; #pragma unroll
;                 for (int kk = 0; kk < 4; ++kk) p1 = __builtin_amdgcn_mfma_f32_32x32x16_bf16(kb[kk], qf[kk], p1, 0, 0, 0);
;                 __builtin_amdgcn_sched_barrier(0);
.Lfar_qk_a1s1:
	ds_read_b128 v[66:69], v183 offset:9216
	ds_read_b128 v[70:73], v183 offset:9248
	ds_read_b128 v[208:211], v183 offset:9280
	ds_read_b128 v[212:215], v183 offset:9312
	s_waitcnt lgkmcnt(2)
	v_mfma_f32_32x32x16_bf16 v[82:97], v[66:69], v[134:137], 0
	v_mfma_f32_32x32x16_bf16 v[82:97], v[70:73], v[130:133], v[82:97]
	ds_read_b128 v[192:195], v183 offset:13824
	ds_read_b128 v[196:199], v183 offset:13856
	ds_read_b128 v[200:203], v183 offset:13888
	ds_read_b128 v[204:207], v183 offset:13920
	s_waitcnt lgkmcnt(4)
	v_mfma_f32_32x32x16_bf16 v[82:97], v[208:211], v[126:129], v[82:97]
	v_mfma_f32_32x32x16_bf16 v[82:97], v[212:215], v[122:125], v[82:97]
	s_waitcnt lgkmcnt(0)
	v_mfma_f32_32x32x16_bf16 v[66:81], v[192:195], v[134:137], 0
	v_mfma_f32_32x32x16_bf16 v[66:81], v[196:199], v[130:133], v[66:81]
	v_mfma_f32_32x32x16_bf16 v[66:81], v[200:203], v[126:129], v[66:81]
	v_mfma_f32_32x32x16_bf16 v[66:81], v[204:207], v[122:125], v[66:81]
	s_branch .Ljoin_qk_a1s1

; __device__ __forceinline__ int crowc(int r) { return (r & 3) + 8 * (r >> 2); }
; template <int D, int DV, bool TAB, bool BITS, int KT> ...
;     ...
;         const int k0 = t * KT + sub * 64;
;         bool active = true;
;         if (TAB) active = (k0 <= qw_hi) && (k0 + 63 >= qw_lo - win);
;         if (active) {
;             const unsigned char* Kl = lds + KOFF + cur * KBUF + sub * 64 * KP; const unsigned char* Vl = lds + VOFF + cur * VBUF + sub * 128;
;             f32x16 p0, p1;
;             unsigned w0 = 0xffffffffu, w1 = 0xffffffffu;
;             if (BITS) { w0 = wq[2 * sub] >> (4 * hi); w1 = wq[2 * sub + 1] >> (4 * hi); }
;             const float nm = -mhat;
;             const int tj = TABN - 1 - TABOFF - qpos + k0 + 4 * hi;
;             constexpr int KG = (D > 64) ? 2 : 4;
;             if (D == 64) {
;                 bf16x8 ka[4], kb[4];
;                 if (TAB) {
; #pragma unroll
;                     for (int r = 0; r < 16; ++r) p0[r] = tabL[tj + crowc(r)]; }
; #pragma unroll
;                 for (int kk = 0; kk < 4; ++kk) ka[kk] = *(const bf16x8*)(Kl + r32 * KP + (kk * 16 + 8 * hi) * 2);
;                 if (TAB) {
; #pragma unroll
;                     for (int r = 0; r < 16; ++r) p1[r] = tabL[tj + 32 + crowc(r)]; }
; #pragma unroll
;                 for (int kk = 0; kk < 4; ++kk) kb[kk] = *(const bf16x8*)(Kl + (32 + r32) * KP + (kk * 16 + 8 * hi) * 2);
;                 __builtin_amdgcn_sched_barrier(0);
; #pragma unroll
;                 for (int r = 0; r < 16; ++r) { if (TAB) p0[r] -= mhat; else p0[r] = nm; if (BITS) { if (!((w0 >> crowc(r)) & 1u)) p0[r] = NEGV; } }
;                 __builtin_amdgcn_sched_barrier(0);
; #pragma unroll
;                 for (int kk = 0; kk < 4; ++kk) p0 = __builtin_amdgcn_mfma_f32_32x32x16_bf16(ka[kk], qf[kk], p0, 0, 0, 0);
; #pragma unroll
;                 for (int r = 0; r < 16; ++r) { if (TAB) p1[r] -= mhat; else p1[r] = nm; if (BITS) { if (!((w1 >> crowc(r)) & 1u)) p1[r] = NEGV; } }
;                 __builtin_amdgcn_sched_barrier(0);
; #pragma unroll
;                 for (int kk = 0; kk < 4; ++kk) p1 = __builtin_amdgcn_mfma_f32_32x32x16_bf16(kb[kk], qf[kk], p1, 0, 0, 0);
;                 __builtin_amdgcn_sched_barrier(0);
.LBB0_345:
	s_mul_i32 s13, s62, 0x4800
	s_add_i32 s12, s64, 0xffffff80
	s_add_i32 s50, s13, 0
	s_mul_i32 s13, s62, 0x8400
	s_cmp_le_i32 s12, s63
	v_add_u32_e32 v182, s13, v175
	s_cselect_b64 s[12:13], -1, 0
	s_add_i32 s51, s64, 0xffffffbf
	s_cmp_ge_i32 s51, s79
	s_cselect_b64 s[52:53], -1, 0
	s_and_b64 s[12:13], s[12:13], s[52:53]
	s_and_b64 vcc, exec, s[12:13]
	v_add3_u32 v183, s50, v176, v0
	s_cbranch_vccz .LBB0_351
	s_cmp_lg_u32 s100, 0
	s_cbranch_scc1 .Lslow_qk_a1s0
	s_add_i32 s12, s64, 0x640
	s_cmp_le_i32 s12, s63
	s_cbranch_scc1 .Lfar_qk_a1s0
	ds_read_b128 v[66:69], v183
	ds_read_b128 v[70:73], v183 offset:32
	ds_read2_b32 v[90:91], v180 offset0:16 offset1:17
	ds_read2_b32 v[92:93], v180 offset0:18 offset1:19
	ds_read2_b32 v[94:95], v180 offset0:24 offset1:25
	ds_read2_b32 v[96:97], v180 offset0:26 offset1:27
	ds_read2_b32 v[82:83], v180 offset1:1
	ds_read2_b32 v[84:85], v180 offset0:2 offset1:3
	ds_read2_b32 v[86:87], v180 offset0:8 offset1:9
	ds_read2_b32 v[88:89], v180 offset0:10 offset1:11
	ds_read_b128 v[208:211], v183 offset:64
	ds_read_b128 v[212:215], v183 offset:96
	s_waitcnt lgkmcnt(2)
	v_mfma_f32_32x32x16_bf16 v[82:97], v[66:69], v[134:137], v[82:97]
	v_mfma_f32_32x32x16_bf16 v[82:97], v[70:73], v[130:133], v[82:97]
	ds_read_b128 v[192:195], v183 offset:4608
	ds_read_b128 v[196:199], v183 offset:4640
	ds_read_b128 v[200:203], v183 offset:4672
	ds_read_b128 v[204:207], v183 offset:4704
	ds_read2_b32 v[66:67], v180 offset0:32 offset1:33
	ds_read2_b32 v[68:69], v180 offset0:34 offset1:35
	ds_read2_b32 v[70:71], v180 offset0:40 offset1:41
	ds_read2_b32 v[72:73], v180 offset0:42 offset1:43
	ds_read2_b32 v[74:75], v180 offset0:48 offset1:49
	ds_read2_b32 v[76:77], v180 offset0:50 offset1:51
	ds_read2_b32 v[78:79], v180 offset0:56 offset1:57
	ds_read2_b32 v[80:81], v180 offset0:58 offset1:59
	s_waitcnt lgkmcnt(12)
	v_mfma_f32_32x32x16_bf16 v[82:97], v[208:211], v[126:129], v[82:97]
	v_mfma_f32_32x32x16_bf16 v[82:97], v[212:215], v[122:125], v[82:97]
	s_waitcnt lgkmcnt(0)
	v_mfma_f32_32x32x16_bf16 v[66:81], v[192:195], v[134:137], v[66:81]
	v_mfma_f32_32x32x16_bf16 v[66:81], v[196:199], v[130:133], v[66:81]
	v_mfma_f32_32x32x16_bf16 v[66:81], v[200:203], v[126:129], v[66:81]
	v_mfma_f32_32x32x16_bf16 v[66:81], v[204:207], v[122:125], v[66:81]

; __device__ __forceinline__ int crowc(int r) { return (r & 3) + 8 * (r >> 2); }
; template <int D, int DV, bool TAB, bool BITS, int KT> ...
;     ...
;         const int k0 = t * KT + sub * 64;
;         bool active = true;
;         if (TAB) active = (k0 <= qw_hi) && (k0 + 63 >= qw_lo - win);
;         if (active) {
;             const unsigned char* Kl = lds + KOFF + cur * KBUF + sub * 64 * KP; const unsigned char* Vl = lds + VOFF + cur * VBUF + sub * 128;
;             f32x16 p0, p1;
;             unsigned w0 = 0xffffffffu, w1 = 0xffffffffu;
;             if (BITS) { w0 = wq[2 * sub] >> (4 * hi); w1 = wq[2 * sub + 1] >> (4 * hi); }
;             const float nm = -mhat;
;             const int tj = TABN - 1 - TABOFF - qpos + k0 + 4 * hi;
;             constexpr int KG = (D > 64) ? 2 : 4;
;             if (D == 64) {
;                 bf16x8 ka[4], kb[4];
;                 if (TAB) {
; #pragma unroll
;                     for (int r = 0; r < 16; ++r) p0[r] = tabL[tj + crowc(r)]; }
; #pragma unroll
;                 for (int kk = 0; kk < 4; ++kk) ka[kk] = *(const bf16x8*)(Kl + r32 * KP + (kk * 16 + 8 * hi) * 2);
;                 if (TAB) {
; #pragma unroll
;                     for (int r = 0; r < 16; ++r) p1[r] = tabL[tj + 32 + crowc(r)]; }
; #pragma unroll
;                 for (int kk = 0; kk < 4; ++kk) kb[kk] = *(const bf16x8*)(Kl + (32 + r32) * KP + (kk * 16 + 8 * hi) * 2);
;                 __builtin_amdgcn_sched_barrier(0);
; #pragma unroll
;                 for (int r = 0; r < 16; ++r) { if (TAB) p0[r] -= mhat; else p0[r] = nm; if (BITS) { if (!((w0 >> crowc(r)) & 1u)) p0[r] = NEGV; } }
;                 __builtin_amdgcn_sched_barrier(0);
; #pragma unroll
;                 for (int kk = 0; kk < 4; ++kk) p0 = __builtin_amdgcn_mfma_f32_32x32x16_bf16(ka[kk], qf[kk], p0, 0, 0, 0);
; #pragma unroll
;                 for (int r = 0; r < 16; ++r) { if (TAB) p1[r] -= mhat; else p1[r] = nm; if (BITS) { if (!((w1 >> crowc(r)) & 1u)) p1[r] = NEGV; } }
;                 __builtin_amdgcn_sched_barrier(0);
; #pragma unroll
;                 for (int kk = 0; kk < 4; ++kk) p1 = __builtin_amdgcn_mfma_f32_32x32x16_bf16(kb[kk], qf[kk], p1, 0, 0, 0);
;                 __builtin_amdgcn_sched_barrier(0);
.Lback_0:
.LBB0_351:
	s_sub_i32 s12, s64, 64
	s_cmp_le_i32 s12, s63
	s_cselect_b64 s[12:13], -1, 0
	s_add_i32 s50, s64, -1
	s_cmp_ge_i32 s50, s79
	s_cselect_b64 s[52:53], -1, 0
	s_and_b64 s[12:13], s[12:13], s[52:53]
	s_andn2_b64 vcc, exec, s[12:13]
	s_cbranch_vccnz .LBB0_357
	s_cmp_lg_u32 s100, 0
	s_cbranch_scc1 .Lslow_qk_a1s1
	s_add_i32 s12, s64, 0x640
	s_cmp_le_i32 s12, s63
	s_cbranch_scc1 .Lfar_qk_a1s1
	ds_read_b128 v[66:69], v183 offset:9216
	ds_read_b128 v[70:73], v183 offset:9248
	ds_read2_b32 v[90:91], v180 offset0:80 offset1:81
	ds_read2_b32 v[92:93], v180 offset0:82 offset1:83
	ds_read2_b32 v[94:95], v180 offset0:88 offset1:89
	ds_read2_b32 v[96:97], v180 offset0:90 offset1:91
	ds_read2_b32 v[82:83], v180 offset0:64 offset1:65
	ds_read2_b32 v[84:85], v180 offset0:66 offset1:67
	ds_read2_b32 v[86:87], v180 offset0:72 offset1:73
	ds_read2_b32 v[88:89], v180 offset0:74 offset1:75
	ds_read_b128 v[208:211], v183 offset:9280
	ds_read_b128 v[212:215], v183 offset:9312
	s_waitcnt lgkmcnt(2)
	v_mfma_f32_32x32x16_bf16 v[82:97], v[66:69], v[134:137], v[82:97]
	v_mfma_f32_32x32x16_bf16 v[82:97], v[70:73], v[130:133], v[82:97]
	ds_read_b128 v[192:195], v183 offset:13824
	ds_read_b128 v[196:199], v183 offset:13856
	ds_read_b128 v[200:203], v183 offset:13888
	ds_read_b128 v[204:207], v183 offset:13920
	ds_read2_b32 v[66:67], v180 offset0:96 offset1:97
	ds_read2_b32 v[68:69], v180 offset0:98 offset1:99
	ds_read2_b32 v[70:71], v180 offset0:104 offset1:105
	ds_read2_b32 v[72:73], v180 offset0:106 offset1:107
	ds_read2_b32 v[74:75], v180 offset0:112 offset1:113
	ds_read2_b32 v[76:77], v180 offset0:114 offset1:115
	ds_read2_b32 v[78:79], v180 offset0:120 offset1:121
	ds_read2_b32 v[80:81], v180 offset0:122 offset1:123
	s_waitcnt lgkmcnt(12)
	v_mfma_f32_32x32x16_bf16 v[82:97], v[208:211], v[126:129], v[82:97]
	v_mfma_f32_32x32x16_bf16 v[82:97], v[212:215], v[122:125], v[82:97]
	s_waitcnt lgkmcnt(0)
	v_mfma_f32_32x32x16_bf16 v[66:81], v[192:195], v[134:137], v[66:81]
	v_mfma_f32_32x32x16_bf16 v[66:81], v[196:199], v[130:133], v[66:81]
	v_mfma_f32_32x32x16_bf16 v[66:81], v[200:203], v[126:129], v[66:81]
	v_mfma_f32_32x32x16_bf16 v[66:81], v[204:207], v[122:125], v[66:81]

; __device__ __forceinline__ int crowc(int r) { return (r & 3) + 8 * (r >> 2); }
; template <int D, int DV, bool TAB, bool BITS, int KT> ...
;     ...
;         const int k0 = t * KT + sub * 64;
;         bool active = true;
;         if (TAB) active = (k0 <= qw_hi) && (k0 + 63 >= qw_lo - win);
;         if (active) {
;             const unsigned char* Kl = lds + KOFF + cur * KBUF + sub * 64 * KP; const unsigned char* Vl = lds + VOFF + cur * VBUF + sub * 128;
;             f32x16 p0, p1;
;             unsigned w0 = 0xffffffffu, w1 = 0xffffffffu;
;             if (BITS) { w0 = wq[2 * sub] >> (4 * hi); w1 = wq[2 * sub + 1] >> (4 * hi); }
;             const float nm = -mhat;
;             const int tj = TABN - 1 - TABOFF - qpos + k0 + 4 * hi;
;             constexpr int KG = (D > 64) ? 2 : 4;
;             if (D == 64) {
;                 bf16x8 ka[4], kb[4];
;                 if (TAB) {
; #pragma unroll
;                     for (int r = 0; r < 16; ++r) p0[r] = tabL[tj + crowc(r)]; }
; #pragma unroll
;                 for (int kk = 0; kk < 4; ++kk) ka[kk] = *(const bf16x8*)(Kl + r32 * KP + (kk * 16 + 8 * hi) * 2);
;                 if (TAB) {
; #pragma unroll
;                     for (int r = 0; r < 16; ++r) p1[r] = tabL[tj + 32 + crowc(r)]; }
; #pragma unroll
;                 for (int kk = 0; kk < 4; ++kk) kb[kk] = *(const bf16x8*)(Kl + (32 + r32) * KP + (kk * 16 + 8 * hi) * 2);
;                 __builtin_amdgcn_sched_barrier(0);
; #pragma unroll
;                 for (int r = 0; r < 16; ++r) { if (TAB) p0[r] -= mhat; else p0[r] = nm; if (BITS) { if (!((w0 >> crowc(r)) & 1u)) p0[r] = NEGV; } }
;                 __builtin_amdgcn_sched_barrier(0);
; #pragma unroll
;                 for (int kk = 0; kk < 4; ++kk) p0 = __builtin_amdgcn_mfma_f32_32x32x16_bf16(ka[kk], qf[kk], p0, 0, 0, 0);
; #pragma unroll
;                 for (int r = 0; r < 16; ++r) { if (TAB) p1[r] -= mhat; else p1[r] = nm; if (BITS) { if (!((w1 >> crowc(r)) & 1u)) p1[r] = NEGV; } }
;                 __builtin_amdgcn_sched_barrier(0);
; #pragma unroll
;                 for (int kk = 0; kk < 4; ++kk) p1 = __builtin_amdgcn_mfma_f32_32x32x16_bf16(kb[kk], qf[kk], p1, 0, 0, 0);
;                 __builtin_amdgcn_sched_barrier(0);
.LBB0_367:
	s_mul_i32 s11, s63, 0x4800
	s_add_i32 s10, s64, 0xffffff80
	s_add_i32 s50, s11, 0
	s_mul_i32 s11, s63, 0x8400
	s_cmp_le_i32 s10, s25
	v_add_u32_e32 v182, s11, v176
	s_cselect_b64 s[10:11], -1, 0
	s_add_i32 s12, s64, 0xffffffbf
	s_cmp_ge_i32 s12, s62
	s_cselect_b64 s[12:13], -1, 0
	s_and_b64 s[10:11], s[10:11], s[12:13]
	s_and_b64 vcc, exec, s[10:11]
	v_add3_u32 v183, s50, v177, v0
	s_cbranch_vccz .LBB0_373
	s_cmp_lg_u32 s100, 0
	s_cbranch_scc1 .Lslow_qk_a2s0
	s_add_i32 s10, s64, 0x640
	s_cmp_le_i32 s10, s25
	s_cbranch_scc1 .Lfar_qk_a2s0
	ds_read_b128 v[66:69], v183
	ds_read_b128 v[70:73], v183 offset:32
	ds_read2_b32 v[90:91], v180 offset0:16 offset1:17
	ds_read2_b32 v[92:93], v180 offset0:18 offset1:19
	ds_read2_b32 v[94:95], v180 offset0:24 offset1:25
	ds_read2_b32 v[96:97], v180 offset0:26 offset1:27
	ds_read2_b32 v[82:83], v180 offset1:1
	ds_read2_b32 v[84:85], v180 offset0:2 offset1:3
	ds_read2_b32 v[86:87], v180 offset0:8 offset1:9
	ds_read2_b32 v[88:89], v180 offset0:10 offset1:11
	ds_read_b128 v[208:211], v183 offset:64
	ds_read_b128 v[212:215], v183 offset:96
	s_waitcnt lgkmcnt(2)
	v_mfma_f32_32x32x16_bf16 v[82:97], v[66:69], v[134:137], v[82:97]
	v_mfma_f32_32x32x16_bf16 v[82:97], v[70:73], v[130:133], v[82:97]
	ds_read_b128 v[192:195], v183 offset:4608
	ds_read_b128 v[196:199], v183 offset:4640
	ds_read_b128 v[200:203], v183 offset:4672
	ds_read_b128 v[204:207], v183 offset:4704
	ds_read2_b32 v[66:67], v180 offset0:32 offset1:33
	ds_read2_b32 v[68:69], v180 offset0:34 offset1:35
	ds_read2_b32 v[70:71], v180 offset0:40 offset1:41
	ds_read2_b32 v[72:73], v180 offset0:42 offset1:43
	ds_read2_b32 v[74:75], v180 offset0:48 offset1:49
	ds_read2_b32 v[76:77], v180 offset0:50 offset1:51
	ds_read2_b32 v[78:79], v180 offset0:56 offset1:57
	ds_read2_b32 v[80:81], v180 offset0:58 offset1:59
	s_waitcnt lgkmcnt(12)
	v_mfma_f32_32x32x16_bf16 v[82:97], v[208:211], v[126:129], v[82:97]
	v_mfma_f32_32x32x16_bf16 v[82:97], v[212:215], v[122:125], v[82:97]
	s_waitcnt lgkmcnt(0)
	v_mfma_f32_32x32x16_bf16 v[66:81], v[192:195], v[134:137], v[66:81]
	v_mfma_f32_32x32x16_bf16 v[66:81], v[196:199], v[130:133], v[66:81]
	v_mfma_f32_32x32x16_bf16 v[66:81], v[200:203], v[126:129], v[66:81]
	v_mfma_f32_32x32x16_bf16 v[66:81], v[204:207], v[122:125], v[66:81]

; __device__ __forceinline__ int crowc(int r) { return (r & 3) + 8 * (r >> 2); }
; template <int D, int DV, bool TAB, bool BITS, int KT> ...
;     ...
;         const int k0 = t * KT + sub * 64;
;         bool active = true;
;         if (TAB) active = (k0 <= qw_hi) && (k0 + 63 >= qw_lo - win);
;         if (active) {
;             const unsigned char* Kl = lds + KOFF + cur * KBUF + sub * 64 * KP; const unsigned char* Vl = lds + VOFF + cur * VBUF + sub * 128;
;             f32x16 p0, p1;
;             unsigned w0 = 0xffffffffu, w1 = 0xffffffffu;
;             if (BITS) { w0 = wq[2 * sub] >> (4 * hi); w1 = wq[2 * sub + 1] >> (4 * hi); }
;             const float nm = -mhat;
;             const int tj = TABN - 1 - TABOFF - qpos + k0 + 4 * hi;
;             constexpr int KG = (D > 64) ? 2 : 4;
;             if (D == 64) {
;                 bf16x8 ka[4], kb[4];
;                 if (TAB) {
; #pragma unroll
;                     for (int r = 0; r < 16; ++r) p0[r] = tabL[tj + crowc(r)]; }
; #pragma unroll
;                 for (int kk = 0; kk < 4; ++kk) ka[kk] = *(const bf16x8*)(Kl + r32 * KP + (kk * 16 + 8 * hi) * 2);
;                 if (TAB) {
; #pragma unroll
;                     for (int r = 0; r < 16; ++r) p1[r] = tabL[tj + 32 + crowc(r)]; }
; #pragma unroll
;                 for (int kk = 0; kk < 4; ++kk) kb[kk] = *(const bf16x8*)(Kl + (32 + r32) * KP + (kk * 16 + 8 * hi) * 2);
;                 __builtin_amdgcn_sched_barrier(0);
; #pragma unroll
;                 for (int r = 0; r < 16; ++r) { if (TAB) p0[r] -= mhat; else p0[r] = nm; if (BITS) { if (!((w0 >> crowc(r)) & 1u)) p0[r] = NEGV; } }
;                 __builtin_amdgcn_sched_barrier(0);
; #pragma unroll
;                 for (int kk = 0; kk < 4; ++kk) p0 = __builtin_amdgcn_mfma_f32_32x32x16_bf16(ka[kk], qf[kk], p0, 0, 0, 0);
; #pragma unroll
;                 for (int r = 0; r < 16; ++r) { if (TAB) p1[r] -= mhat; else p1[r] = nm; if (BITS) { if (!((w1 >> crowc(r)) & 1u)) p1[r] = NEGV; } }
;                 __builtin_amdgcn_sched_barrier(0);
; #pragma unroll
;                 for (int kk = 0; kk < 4; ++kk) p1 = __builtin_amdgcn_mfma_f32_32x32x16_bf16(kb[kk], qf[kk], p1, 0, 0, 0);
;                 __builtin_amdgcn_sched_barrier(0);
.Lback_2:
.LBB0_373:
	s_sub_i32 s10, s64, 64
	s_cmp_le_i32 s10, s25
	s_cselect_b64 s[10:11], -1, 0
	s_add_i32 s12, s64, -1
	s_cmp_ge_i32 s12, s62
	s_cselect_b64 s[12:13], -1, 0
	s_and_b64 s[10:11], s[10:11], s[12:13]
	s_andn2_b64 vcc, exec, s[10:11]
	s_cbranch_vccnz .LBB0_379
	s_cmp_lg_u32 s100, 0
	s_cbranch_scc1 .Lslow_qk_a2s1
	s_add_i32 s10, s64, 0x640
	s_cmp_le_i32 s10, s25
	s_cbranch_scc1 .Lfar_qk_a2s1
	ds_read_b128 v[66:69], v183 offset:9216
	ds_read_b128 v[70:73], v183 offset:9248
	ds_read2_b32 v[90:91], v180 offset0:80 offset1:81
	ds_read2_b32 v[92:93], v180 offset0:82 offset1:83
	ds_read2_b32 v[94:95], v180 offset0:88 offset1:89
	ds_read2_b32 v[96:97], v180 offset0:90 offset1:91
	ds_read2_b32 v[82:83], v180 offset0:64 offset1:65
	ds_read2_b32 v[84:85], v180 offset0:66 offset1:67
	ds_read2_b32 v[86:87], v180 offset0:72 offset1:73
	ds_read2_b32 v[88:89], v180 offset0:74 offset1:75
	ds_read_b128 v[208:211], v183 offset:9280
	ds_read_b128 v[212:215], v183 offset:9312
	s_waitcnt lgkmcnt(2)
	v_mfma_f32_32x32x16_bf16 v[82:97], v[66:69], v[134:137], v[82:97]
	v_mfma_f32_32x32x16_bf16 v[82:97], v[70:73], v[130:133], v[82:97]
	ds_read_b128 v[192:195], v183 offset:13824
	ds_read_b128 v[196:199], v183 offset:13856
	ds_read_b128 v[200:203], v183 offset:13888
	ds_read_b128 v[204:207], v183 offset:13920
	ds_read2_b32 v[66:67], v180 offset0:96 offset1:97
	ds_read2_b32 v[68:69], v180 offset0:98 offset1:99
	ds_read2_b32 v[70:71], v180 offset0:104 offset1:105
	ds_read2_b32 v[72:73], v180 offset0:106 offset1:107
	ds_read2_b32 v[74:75], v180 offset0:112 offset1:113
	ds_read2_b32 v[76:77], v180 offset0:114 offset1:115
	ds_read2_b32 v[78:79], v180 offset0:120 offset1:121
	ds_read2_b32 v[80:81], v180 offset0:122 offset1:123
	s_waitcnt lgkmcnt(12)
	v_mfma_f32_32x32x16_bf16 v[82:97], v[208:211], v[126:129], v[82:97]
	v_mfma_f32_32x32x16_bf16 v[82:97], v[212:215], v[122:125], v[82:97]
	s_waitcnt lgkmcnt(0)
	v_mfma_f32_32x32x16_bf16 v[66:81], v[192:195], v[134:137], v[66:81]
	v_mfma_f32_32x32x16_bf16 v[66:81], v[196:199], v[130:133], v[66:81]
	v_mfma_f32_32x32x16_bf16 v[66:81], v[200:203], v[126:129], v[66:81]
	v_mfma_f32_32x32x16_bf16 v[66:81], v[204:207], v[122:125], v[66:81]

; __device__ __forceinline__ int crowc(int r) { return (r & 3) + 8 * (r >> 2); }
; template <int D, int DV, bool TAB, bool BITS, int KT> ...
;     ...
;             if (D == 64) {
;                 bf16x8 ka[4], kb[4];
;                 if (TAB) {
; #pragma unroll
;                     for (int r = 0; r < 16; ++r) p0[r] = tabL[tj + crowc(r)]; }
; #pragma unroll
;                 for (int kk = 0; kk < 4; ++kk) ka[kk] = *(const bf16x8*)(Kl + r32 * KP + (kk * 16 + 8 * hi) * 2);
;                 if (TAB) {
; #pragma unroll
;                     for (int r = 0; r < 16; ++r) p1[r] = tabL[tj + 32 + crowc(r)]; }
; #pragma unroll
;                 for (int kk = 0; kk < 4; ++kk) kb[kk] = *(const bf16x8*)(Kl + (32 + r32) * KP + (kk * 16 + 8 * hi) * 2);
;                 __builtin_amdgcn_sched_barrier(0);
; #pragma unroll
;                 for (int r = 0; r < 16; ++r) { if (TAB) p0[r] -= mhat; else p0[r] = nm; if (BITS) { if (!((w0 >> crowc(r)) & 1u)) p0[r] = NEGV; } }
;                 __builtin_amdgcn_sched_barrier(0);
; #pragma unroll
;                 for (int kk = 0; kk < 4; ++kk) p0 = __builtin_amdgcn_mfma_f32_32x32x16_bf16(ka[kk], qf[kk], p0, 0, 0, 0);
; #pragma unroll
;                 for (int r = 0; r < 16; ++r) { if (TAB) p1[r] -= mhat; else p1[r] = nm; if (BITS) { if (!((w1 >> crowc(r)) & 1u)) p1[r] = NEGV; } }
;                 __builtin_amdgcn_sched_barrier(0);
; #pragma unroll
;                 for (int kk = 0; kk < 4; ++kk) p1 = __builtin_amdgcn_mfma_f32_32x32x16_bf16(kb[kk], qf[kk], p1, 0, 0, 0);
;                 __builtin_amdgcn_sched_barrier(0);
.Lfar_qk_c0:
	ds_read_b128 v[142:145], v141
	ds_read_b128 v[146:149], v141 offset:32
	ds_read_b128 v[150:153], v141 offset:64
	ds_read_b128 v[154:157], v141 offset:96
	ds_read_b128 v[158:161], v141 offset:4608
	ds_read_b128 v[162:165], v141 offset:4640
	ds_read_b128 v[166:169], v141 offset:4672
	ds_read_b128 v[170:173], v141 offset:4704
	v_lshrrev_b32_e32 v174, v134, v102
	v_lshrrev_b32_e32 v175, v134, v103
	v_bfe_i32 v176, v174, 0, 1
	v_bfe_i32 v177, v174, 1, 1
	v_bfe_i32 v178, v174, 2, 1
	v_bfe_i32 v179, v174, 3, 1
	v_bfi_b32 v50, v176, 0, v237
	v_bfi_b32 v51, v177, 0, v237
	v_bfi_b32 v52, v178, 0, v237
	v_bfi_b32 v53, v179, 0, v237
	v_bfe_i32 v176, v174, 8, 1
	v_bfe_i32 v177, v174, 9, 1
	v_bfe_i32 v178, v174, 10, 1
	v_bfe_i32 v179, v174, 11, 1
	v_bfi_b32 v54, v176, 0, v237
	v_bfi_b32 v55, v177, 0, v237
	v_bfi_b32 v56, v178, 0, v237
	v_bfi_b32 v57, v179, 0, v237
	v_bfe_i32 v176, v174, 16, 1
	v_bfe_i32 v177, v174, 17, 1
	v_bfe_i32 v178, v174, 18, 1
	v_bfe_i32 v179, v174, 19, 1
	v_bfi_b32 v58, v176, 0, v237
	v_bfi_b32 v59, v177, 0, v237
	v_bfi_b32 v60, v178, 0, v237
	v_bfi_b32 v61, v179, 0, v237
	v_bfe_i32 v176, v174, 24, 1
	v_bfe_i32 v177, v174, 25, 1
	v_bfe_i32 v178, v174, 26, 1
	v_bfe_i32 v179, v174, 27, 1
	v_bfi_b32 v62, v176, 0, v237
	v_bfi_b32 v63, v177, 0, v237
	v_bfi_b32 v64, v178, 0, v237
	v_bfi_b32 v65, v179, 0, v237
	v_bfe_i32 v176, v175, 0, 1
	v_bfe_i32 v177, v175, 1, 1
	v_bfe_i32 v178, v175, 2, 1
	v_bfe_i32 v179, v175, 3, 1
	v_bfi_b32 v34, v176, 0, v237
	v_bfi_b32 v35, v177, 0, v237
	v_bfi_b32 v36, v178, 0, v237
	v_bfi_b32 v37, v179, 0, v237
	v_bfe_i32 v176, v175, 8, 1
	v_bfe_i32 v177, v175, 9, 1
	v_bfe_i32 v178, v175, 10, 1
	v_bfe_i32 v179, v175, 11, 1
	v_bfi_b32 v38, v176, 0, v237
	v_bfi_b32 v39, v177, 0, v237
	v_bfi_b32 v40, v178, 0, v237
	v_bfi_b32 v41, v179, 0, v237
	v_bfe_i32 v176, v175, 16, 1
	v_bfe_i32 v177, v175, 17, 1
	v_bfe_i32 v178, v175, 18, 1
	v_bfe_i32 v179, v175, 19, 1
	v_bfi_b32 v42, v176, 0, v237
	v_bfi_b32 v43, v177, 0, v237
	v_bfi_b32 v44, v178, 0, v237
	v_bfi_b32 v45, v179, 0, v237
	v_bfe_i32 v176, v175, 24, 1
	v_bfe_i32 v177, v175, 25, 1
	v_bfe_i32 v178, v175, 26, 1
	v_bfe_i32 v179, v175, 27, 1
	v_bfi_b32 v46, v176, 0, v237
	v_bfi_b32 v47, v177, 0, v237
	v_bfi_b32 v48, v178, 0, v237
	v_bfi_b32 v49, v179, 0, v237
	s_nop 1
	s_waitcnt lgkmcnt(3)
	v_mfma_f32_32x32x16_bf16 v[34:49], v[158:161], v[94:97], v[34:49]
	v_mfma_f32_32x32x16_bf16 v[50:65], v[142:145], v[94:97], v[50:65]
	s_waitcnt lgkmcnt(2)
	v_mfma_f32_32x32x16_bf16 v[34:49], v[162:165], v[90:93], v[34:49]
	v_mfma_f32_32x32x16_bf16 v[50:65], v[146:149], v[90:93], v[50:65]
	s_waitcnt lgkmcnt(1)
	v_mfma_f32_32x32x16_bf16 v[34:49], v[166:169], v[86:89], v[34:49]
	v_mfma_f32_32x32x16_bf16 v[50:65], v[150:153], v[86:89], v[50:65]
	s_waitcnt lgkmcnt(0)
	v_mfma_f32_32x32x16_bf16 v[34:49], v[170:173], v[82:85], v[34:49]
	v_mfma_f32_32x32x16_bf16 v[50:65], v[154:157], v[82:85], v[50:65]
	s_nop 11
	s_branch .Ljoin_qk_c0

; __device__ __forceinline__ int crowc(int r) { return (r & 3) + 8 * (r >> 2); }
; template <int D, int DV, bool TAB, bool BITS, int KT> ...
;     ...
;             if (D == 64) {
;                 bf16x8 ka[4], kb[4];
;                 if (TAB) {
; #pragma unroll
;                     for (int r = 0; r < 16; ++r) p0[r] = tabL[tj + crowc(r)]; }
; #pragma unroll
;                 for (int kk = 0; kk < 4; ++kk) ka[kk] = *(const bf16x8*)(Kl + r32 * KP + (kk * 16 + 8 * hi) * 2);
;                 if (TAB) {
; #pragma unroll
;                     for (int r = 0; r < 16; ++r) p1[r] = tabL[tj + 32 + crowc(r)]; }
; #pragma unroll
;                 for (int kk = 0; kk < 4; ++kk) kb[kk] = *(const bf16x8*)(Kl + (32 + r32) * KP + (kk * 16 + 8 * hi) * 2);
;                 __builtin_amdgcn_sched_barrier(0);
; #pragma unroll
;                 for (int r = 0; r < 16; ++r) { if (TAB) p0[r] -= mhat; else p0[r] = nm; if (BITS) { if (!((w0 >> crowc(r)) & 1u)) p0[r] = NEGV; } }
;                 __builtin_amdgcn_sched_barrier(0);
; #pragma unroll
;                 for (int kk = 0; kk < 4; ++kk) p0 = __builtin_amdgcn_mfma_f32_32x32x16_bf16(ka[kk], qf[kk], p0, 0, 0, 0);
; #pragma unroll
;                 for (int r = 0; r < 16; ++r) { if (TAB) p1[r] -= mhat; else p1[r] = nm; if (BITS) { if (!((w1 >> crowc(r)) & 1u)) p1[r] = NEGV; } }
;                 __builtin_amdgcn_sched_barrier(0);
; #pragma unroll
;                 for (int kk = 0; kk < 4; ++kk) p1 = __builtin_amdgcn_mfma_f32_32x32x16_bf16(kb[kk], qf[kk], p1, 0, 0, 0);
;                 __builtin_amdgcn_sched_barrier(0);
.Lfar_qk_c1:
	ds_read_b128 v[142:145], v141 offset:9216
	ds_read_b128 v[146:149], v141 offset:9248
	ds_read_b128 v[150:153], v141 offset:9280
	ds_read_b128 v[154:157], v141 offset:9312
	ds_read_b128 v[158:161], v141 offset:13824
	ds_read_b128 v[162:165], v141 offset:13856
	ds_read_b128 v[166:169], v141 offset:13888
	ds_read_b128 v[170:173], v141 offset:13920
	v_lshrrev_b32_e32 v174, v134, v104
	v_lshrrev_b32_e32 v175, v134, v105
	v_bfe_i32 v176, v174, 0, 1
	v_bfe_i32 v177, v174, 1, 1
	v_bfe_i32 v178, v174, 2, 1
	v_bfe_i32 v179, v174, 3, 1
	v_bfi_b32 v50, v176, 0, v237
	v_bfi_b32 v51, v177, 0, v237
	v_bfi_b32 v52, v178, 0, v237
	v_bfi_b32 v53, v179, 0, v237
	v_bfe_i32 v176, v174, 8, 1
	v_bfe_i32 v177, v174, 9, 1
	v_bfe_i32 v178, v174, 10, 1
	v_bfe_i32 v179, v174, 11, 1
	v_bfi_b32 v54, v176, 0, v237
	v_bfi_b32 v55, v177, 0, v237
	v_bfi_b32 v56, v178, 0, v237
	v_bfi_b32 v57, v179, 0, v237
	v_bfe_i32 v176, v174, 16, 1
	v_bfe_i32 v177, v174, 17, 1
	v_bfe_i32 v178, v174, 18, 1
	v_bfe_i32 v179, v174, 19, 1
	v_bfi_b32 v58, v176, 0, v237
	v_bfi_b32 v59, v177, 0, v237
	v_bfi_b32 v60, v178, 0, v237
	v_bfi_b32 v61, v179, 0, v237
	v_bfe_i32 v176, v174, 24, 1
	v_bfe_i32 v177, v174, 25, 1
	v_bfe_i32 v178, v174, 26, 1
	v_bfe_i32 v179, v174, 27, 1
	v_bfi_b32 v62, v176, 0, v237
	v_bfi_b32 v63, v177, 0, v237
	v_bfi_b32 v64, v178, 0, v237
	v_bfi_b32 v65, v179, 0, v237
	v_bfe_i32 v176, v175, 0, 1
	v_bfe_i32 v177, v175, 1, 1
	v_bfe_i32 v178, v175, 2, 1
	v_bfe_i32 v179, v175, 3, 1
	v_bfi_b32 v34, v176, 0, v237
	v_bfi_b32 v35, v177, 0, v237
	v_bfi_b32 v36, v178, 0, v237
	v_bfi_b32 v37, v179, 0, v237
	v_bfe_i32 v176, v175, 8, 1
	v_bfe_i32 v177, v175, 9, 1
	v_bfe_i32 v178, v175, 10, 1
	v_bfe_i32 v179, v175, 11, 1
	v_bfi_b32 v38, v176, 0, v237
	v_bfi_b32 v39, v177, 0, v237
	v_bfi_b32 v40, v178, 0, v237
	v_bfi_b32 v41, v179, 0, v237
	v_bfe_i32 v176, v175, 16, 1
	v_bfe_i32 v177, v175, 17, 1
	v_bfe_i32 v178, v175, 18, 1
	v_bfe_i32 v179, v175, 19, 1
	v_bfi_b32 v42, v176, 0, v237
	v_bfi_b32 v43, v177, 0, v237
	v_bfi_b32 v44, v178, 0, v237
	v_bfi_b32 v45, v179, 0, v237
	v_bfe_i32 v176, v175, 24, 1
	v_bfe_i32 v177, v175, 25, 1
	v_bfe_i32 v178, v175, 26, 1
	v_bfe_i32 v179, v175, 27, 1
	v_bfi_b32 v46, v176, 0, v237
	v_bfi_b32 v47, v177, 0, v237
	v_bfi_b32 v48, v178, 0, v237
	v_bfi_b32 v49, v179, 0, v237
	s_nop 1
	s_waitcnt lgkmcnt(3)
	v_mfma_f32_32x32x16_bf16 v[34:49], v[158:161], v[94:97], v[34:49]
	v_mfma_f32_32x32x16_bf16 v[50:65], v[142:145], v[94:97], v[50:65]
	s_waitcnt lgkmcnt(2)
	v_mfma_f32_32x32x16_bf16 v[34:49], v[162:165], v[90:93], v[34:49]
	v_mfma_f32_32x32x16_bf16 v[50:65], v[146:149], v[90:93], v[50:65]
	s_waitcnt lgkmcnt(1)
	v_mfma_f32_32x32x16_bf16 v[34:49], v[166:169], v[86:89], v[34:49]
	v_mfma_f32_32x32x16_bf16 v[50:65], v[150:153], v[86:89], v[50:65]
	s_waitcnt lgkmcnt(0)
	v_mfma_f32_32x32x16_bf16 v[34:49], v[170:173], v[82:85], v[34:49]
	v_mfma_f32_32x32x16_bf16 v[50:65], v[154:157], v[82:85], v[50:65]
	s_nop 11
	s_branch .Ljoin_qk_c1

; __device__ __forceinline__ int crowc(int r) { return (r & 3) + 8 * (r >> 2); }
; template <int D, int DV, bool TAB, bool BITS, int KT> ...
;     ...
;         const int k0 = t * KT + sub * 64;
;         bool active = true;
;         if (TAB) active = (k0 <= qw_hi) && (k0 + 63 >= qw_lo - win);
;         if (active) {
;             const unsigned char* Kl = lds + KOFF + cur * KBUF + sub * 64 * KP; const unsigned char* Vl = lds + VOFF + cur * VBUF + sub * 128;
;             f32x16 p0, p1;
;             unsigned w0 = 0xffffffffu, w1 = 0xffffffffu;
;             if (BITS) { w0 = wq[2 * sub] >> (4 * hi); w1 = wq[2 * sub + 1] >> (4 * hi); }
;             const float nm = -mhat;
;             const int tj = TABN - 1 - TABOFF - qpos + k0 + 4 * hi;
;             constexpr int KG = (D > 64) ? 2 : 4;
;             if (D == 64) {
;                 bf16x8 ka[4], kb[4];
;                 if (TAB) {
; #pragma unroll
;                     for (int r = 0; r < 16; ++r) p0[r] = tabL[tj + crowc(r)]; }
; #pragma unroll
;                 for (int kk = 0; kk < 4; ++kk) ka[kk] = *(const bf16x8*)(Kl + r32 * KP + (kk * 16 + 8 * hi) * 2);
;                 if (TAB) {
; #pragma unroll
;                     for (int r = 0; r < 16; ++r) p1[r] = tabL[tj + 32 + crowc(r)]; }
; #pragma unroll
;                 for (int kk = 0; kk < 4; ++kk) kb[kk] = *(const bf16x8*)(Kl + (32 + r32) * KP + (kk * 16 + 8 * hi) * 2);
;                 __builtin_amdgcn_sched_barrier(0);
; #pragma unroll
;                 for (int r = 0; r < 16; ++r) { if (TAB) p0[r] -= mhat; else p0[r] = nm; if (BITS) { if (!((w0 >> crowc(r)) & 1u)) p0[r] = NEGV; } }
;                 __builtin_amdgcn_sched_barrier(0);
; #pragma unroll
;                 for (int kk = 0; kk < 4; ++kk) p0 = __builtin_amdgcn_mfma_f32_32x32x16_bf16(ka[kk], qf[kk], p0, 0, 0, 0);
; #pragma unroll
;                 for (int r = 0; r < 16; ++r) { if (TAB) p1[r] -= mhat; else p1[r] = nm; if (BITS) { if (!((w1 >> crowc(r)) & 1u)) p1[r] = NEGV; } }
;                 __builtin_amdgcn_sched_barrier(0);
; #pragma unroll
;                 for (int kk = 0; kk < 4; ++kk) p1 = __builtin_amdgcn_mfma_f32_32x32x16_bf16(kb[kk], qf[kk], p1, 0, 0, 0);
;                 __builtin_amdgcn_sched_barrier(0);
.LBB0_952:
	s_mul_i32 s12, s72, 0x4800
	s_add_i32 s9, s64, 0xffffff80
	s_add_i32 s50, s12, 0
	s_mul_i32 s12, s72, 0x4200
	s_cmp_le_i32 s9, s73
	v_add_u32_e32 v140, s12, v132
	s_cselect_b64 s[12:13], -1, 0
	s_add_i32 s9, s64, 0xffffffbf
	s_cmp_ge_i32 s9, s74
	s_cselect_b64 s[52:53], -1, 0
	s_and_b64 s[12:13], s[12:13], s[52:53]
	s_and_b64 vcc, exec, s[12:13]
	v_add3_u32 v141, s50, v135, v0
	s_cbranch_vccz .LBB0_958
	s_cmp_lg_u32 s100, 0
	s_cbranch_scc1 .Lslow_qk_c0
	s_add_i32 s9, s64, 0x640
	s_cmp_le_i32 s9, s73
	s_cbranch_scc1 .Lfar_qk_c0
	ds_read2_b32 v[50:51], v138 offset1:1
	ds_read2_b32 v[52:53], v138 offset0:2 offset1:3
	ds_read2_b32 v[54:55], v138 offset0:8 offset1:9
	ds_read2_b32 v[56:57], v138 offset0:10 offset1:11
	ds_read2_b32 v[58:59], v138 offset0:16 offset1:17
	ds_read2_b32 v[60:61], v138 offset0:18 offset1:19
	ds_read2_b32 v[62:63], v138 offset0:24 offset1:25
	ds_read2_b32 v[64:65], v138 offset0:26 offset1:27
	ds_read_b128 v[142:145], v141
	ds_read_b128 v[146:149], v141 offset:32
	ds_read_b128 v[150:153], v141 offset:64
	ds_read_b128 v[154:157], v141 offset:96
	ds_read2_b32 v[34:35], v138 offset0:32 offset1:33
	ds_read2_b32 v[36:37], v138 offset0:34 offset1:35
	ds_read2_b32 v[38:39], v138 offset0:40 offset1:41
	ds_read2_b32 v[40:41], v138 offset0:42 offset1:43
	ds_read2_b32 v[42:43], v138 offset0:48 offset1:49
	ds_read2_b32 v[44:45], v138 offset0:50 offset1:51
	ds_read2_b32 v[46:47], v138 offset0:56 offset1:57
	ds_read2_b32 v[48:49], v138 offset0:58 offset1:59
	ds_read_b128 v[158:161], v141 offset:4608
	ds_read_b128 v[162:165], v141 offset:4640
	ds_read_b128 v[166:169], v141 offset:4672
	ds_read_b128 v[170:173], v141 offset:4704
	v_lshrrev_b32_e32 v174, v134, v102
	v_lshrrev_b32_e32 v175, v134, v103
	s_waitcnt lgkmcnt(15)
	v_bfe_i32 v176, v174, 0, 1
	v_bfe_i32 v177, v174, 1, 1
	v_bfe_i32 v178, v174, 2, 1
	v_bfe_i32 v179, v174, 3, 1
	v_bfi_b32 v50, v176, v50, v237
	v_bfi_b32 v51, v177, v51, v237
	v_bfi_b32 v52, v178, v52, v237
	v_bfi_b32 v53, v179, v53, v237
	v_bfe_i32 v176, v174, 8, 1
	v_bfe_i32 v177, v174, 9, 1
	v_bfe_i32 v178, v174, 10, 1
	v_bfe_i32 v179, v174, 11, 1
	v_bfi_b32 v54, v176, v54, v237
	v_bfi_b32 v55, v177, v55, v237
	v_bfi_b32 v56, v178, v56, v237
	v_bfi_b32 v57, v179, v57, v237
	v_bfe_i32 v176, v174, 16, 1
	v_bfe_i32 v177, v174, 17, 1
	v_bfe_i32 v178, v174, 18, 1
	v_bfe_i32 v179, v174, 19, 1
	v_bfi_b32 v58, v176, v58, v237
	v_bfi_b32 v59, v177, v59, v237
	v_bfi_b32 v60, v178, v60, v237
	v_bfi_b32 v61, v179, v61, v237
	v_bfe_i32 v176, v174, 24, 1
	v_bfe_i32 v177, v174, 25, 1
	v_bfe_i32 v178, v174, 26, 1
	v_bfe_i32 v179, v174, 27, 1
	v_bfi_b32 v62, v176, v62, v237
	v_bfi_b32 v63, v177, v63, v237
	v_bfi_b32 v64, v178, v64, v237
	v_bfi_b32 v65, v179, v65, v237
	s_waitcnt lgkmcnt(4)
	v_bfe_i32 v176, v175, 0, 1
	v_bfe_i32 v177, v175, 1, 1
	v_bfe_i32 v178, v175, 2, 1
	v_bfe_i32 v179, v175, 3, 1
	v_bfi_b32 v34, v176, v34, v237
	v_bfi_b32 v35, v177, v35, v237
	v_bfi_b32 v36, v178, v36, v237
	v_bfi_b32 v37, v179, v37, v237
	v_bfe_i32 v176, v175, 8, 1
	v_bfe_i32 v177, v175, 9, 1
	v_bfe_i32 v178, v175, 10, 1
	v_bfe_i32 v179, v175, 11, 1
	v_bfi_b32 v38, v176, v38, v237
	v_bfi_b32 v39, v177, v39, v237
	v_bfi_b32 v40, v178, v40, v237
	v_bfi_b32 v41, v179, v41, v237
	v_bfe_i32 v176, v175, 16, 1
	v_bfe_i32 v177, v175, 17, 1
	v_bfe_i32 v178, v175, 18, 1
	v_bfe_i32 v179, v175, 19, 1
	v_bfi_b32 v42, v176, v42, v237
	v_bfi_b32 v43, v177, v43, v237
	v_bfi_b32 v44, v178, v44, v237
	v_bfi_b32 v45, v179, v45, v237
	v_bfe_i32 v176, v175, 24, 1
	v_bfe_i32 v177, v175, 25, 1
	v_bfe_i32 v178, v175, 26, 1
	v_bfe_i32 v179, v175, 27, 1
	v_bfi_b32 v46, v176, v46, v237
	v_bfi_b32 v47, v177, v47, v237
	v_bfi_b32 v48, v178, v48, v237
	v_bfi_b32 v49, v179, v49, v237
	s_nop 1
	s_waitcnt lgkmcnt(3)
	v_mfma_f32_32x32x16_bf16 v[34:49], v[158:161], v[94:97], v[34:49]
	v_mfma_f32_32x32x16_bf16 v[50:65], v[142:145], v[94:97], v[50:65]
	s_waitcnt lgkmcnt(2)
	v_mfma_f32_32x32x16_bf16 v[34:49], v[162:165], v[90:93], v[34:49]
	v_mfma_f32_32x32x16_bf16 v[50:65], v[146:149], v[90:93], v[50:65]
	s_waitcnt lgkmcnt(1)
	v_mfma_f32_32x32x16_bf16 v[34:49], v[166:169], v[86:89], v[34:49]
	v_mfma_f32_32x32x16_bf16 v[50:65], v[150:153], v[86:89], v[50:65]
	s_waitcnt lgkmcnt(0)
	v_mfma_f32_32x32x16_bf16 v[34:49], v[170:173], v[82:85], v[34:49]
	v_mfma_f32_32x32x16_bf16 v[50:65], v[154:157], v[82:85], v[50:65]
	s_nop 11

; __device__ __forceinline__ int crowc(int r) { return (r & 3) + 8 * (r >> 2); }
; template <int D, int DV, bool TAB, bool BITS, int KT> ...
;     ...
;         const int k0 = t * KT + sub * 64;
;         bool active = true;
;         if (TAB) active = (k0 <= qw_hi) && (k0 + 63 >= qw_lo - win);
;         if (active) {
;             const unsigned char* Kl = lds + KOFF + cur * KBUF + sub * 64 * KP; const unsigned char* Vl = lds + VOFF + cur * VBUF + sub * 128;
;             f32x16 p0, p1;
;             unsigned w0 = 0xffffffffu, w1 = 0xffffffffu;
;             if (BITS) { w0 = wq[2 * sub] >> (4 * hi); w1 = wq[2 * sub + 1] >> (4 * hi); }
;             const float nm = -mhat;
;             const int tj = TABN - 1 - TABOFF - qpos + k0 + 4 * hi;
;             constexpr int KG = (D > 64) ? 2 : 4;
;             if (D == 64) {
;                 bf16x8 ka[4], kb[4];
;                 if (TAB) {
; #pragma unroll
;                     for (int r = 0; r < 16; ++r) p0[r] = tabL[tj + crowc(r)]; }
; #pragma unroll
;                 for (int kk = 0; kk < 4; ++kk) ka[kk] = *(const bf16x8*)(Kl + r32 * KP + (kk * 16 + 8 * hi) * 2);
;                 if (TAB) {
; #pragma unroll
;                     for (int r = 0; r < 16; ++r) p1[r] = tabL[tj + 32 + crowc(r)]; }
; #pragma unroll
;                 for (int kk = 0; kk < 4; ++kk) kb[kk] = *(const bf16x8*)(Kl + (32 + r32) * KP + (kk * 16 + 8 * hi) * 2);
;                 __builtin_amdgcn_sched_barrier(0);
; #pragma unroll
;                 for (int r = 0; r < 16; ++r) { if (TAB) p0[r] -= mhat; else p0[r] = nm; if (BITS) { if (!((w0 >> crowc(r)) & 1u)) p0[r] = NEGV; } }
;                 __builtin_amdgcn_sched_barrier(0);
; #pragma unroll
;                 for (int kk = 0; kk < 4; ++kk) p0 = __builtin_amdgcn_mfma_f32_32x32x16_bf16(ka[kk], qf[kk], p0, 0, 0, 0);
; #pragma unroll
;                 for (int r = 0; r < 16; ++r) { if (TAB) p1[r] -= mhat; else p1[r] = nm; if (BITS) { if (!((w1 >> crowc(r)) & 1u)) p1[r] = NEGV; } }
;                 __builtin_amdgcn_sched_barrier(0);
; #pragma unroll
;                 for (int kk = 0; kk < 4; ++kk) p1 = __builtin_amdgcn_mfma_f32_32x32x16_bf16(kb[kk], qf[kk], p1, 0, 0, 0);
;                 __builtin_amdgcn_sched_barrier(0);
.Lback_6:
.LBB0_958:
	s_sub_i32 s9, s64, 64
	s_cmp_le_i32 s9, s73
	s_cselect_b64 s[12:13], -1, 0
	s_add_i32 s9, s64, -1
	s_cmp_ge_i32 s9, s74
	s_cselect_b64 s[52:53], -1, 0
	s_and_b64 s[12:13], s[12:13], s[52:53]
	s_andn2_b64 vcc, exec, s[12:13]
	s_cbranch_vccnz .LBB0_964
	s_cmp_lg_u32 s100, 0
	s_cbranch_scc1 .Lslow_qk_c1
	s_add_i32 s9, s64, 0x640
	s_cmp_le_i32 s9, s73
	s_cbranch_scc1 .Lfar_qk_c1
	ds_read2_b32 v[50:51], v138 offset0:64 offset1:65
	ds_read2_b32 v[52:53], v138 offset0:66 offset1:67
	ds_read2_b32 v[54:55], v138 offset0:72 offset1:73
	ds_read2_b32 v[56:57], v138 offset0:74 offset1:75
	ds_read2_b32 v[58:59], v138 offset0:80 offset1:81
	ds_read2_b32 v[60:61], v138 offset0:82 offset1:83
	ds_read2_b32 v[62:63], v138 offset0:88 offset1:89
	ds_read2_b32 v[64:65], v138 offset0:90 offset1:91
	ds_read_b128 v[142:145], v141 offset:9216
	ds_read_b128 v[146:149], v141 offset:9248
	ds_read_b128 v[150:153], v141 offset:9280
	ds_read_b128 v[154:157], v141 offset:9312
	ds_read2_b32 v[34:35], v138 offset0:96 offset1:97
	ds_read2_b32 v[36:37], v138 offset0:98 offset1:99
	ds_read2_b32 v[38:39], v138 offset0:104 offset1:105
	ds_read2_b32 v[40:41], v138 offset0:106 offset1:107
	ds_read2_b32 v[42:43], v138 offset0:112 offset1:113
	ds_read2_b32 v[44:45], v138 offset0:114 offset1:115
	ds_read2_b32 v[46:47], v138 offset0:120 offset1:121
	ds_read2_b32 v[48:49], v138 offset0:122 offset1:123
	ds_read_b128 v[158:161], v141 offset:13824
	ds_read_b128 v[162:165], v141 offset:13856
	ds_read_b128 v[166:169], v141 offset:13888
	ds_read_b128 v[170:173], v141 offset:13920
	v_lshrrev_b32_e32 v174, v134, v104
	v_lshrrev_b32_e32 v175, v134, v105
	s_waitcnt lgkmcnt(15)
	v_bfe_i32 v176, v174, 0, 1
	v_bfe_i32 v177, v174, 1, 1
	v_bfe_i32 v178, v174, 2, 1
	v_bfe_i32 v179, v174, 3, 1
	v_bfi_b32 v50, v176, v50, v237
	v_bfi_b32 v51, v177, v51, v237
	v_bfi_b32 v52, v178, v52, v237
	v_bfi_b32 v53, v179, v53, v237
	v_bfe_i32 v176, v174, 8, 1
	v_bfe_i32 v177, v174, 9, 1
	v_bfe_i32 v178, v174, 10, 1
	v_bfe_i32 v179, v174, 11, 1
	v_bfi_b32 v54, v176, v54, v237
	v_bfi_b32 v55, v177, v55, v237
	v_bfi_b32 v56, v178, v56, v237
	v_bfi_b32 v57, v179, v57, v237
	v_bfe_i32 v176, v174, 16, 1
	v_bfe_i32 v177, v174, 17, 1
	v_bfe_i32 v178, v174, 18, 1
	v_bfe_i32 v179, v174, 19, 1
	v_bfi_b32 v58, v176, v58, v237
	v_bfi_b32 v59, v177, v59, v237
	v_bfi_b32 v60, v178, v60, v237
	v_bfi_b32 v61, v179, v61, v237
	v_bfe_i32 v176, v174, 24, 1
	v_bfe_i32 v177, v174, 25, 1
	v_bfe_i32 v178, v174, 26, 1
	v_bfe_i32 v179, v174, 27, 1
	v_bfi_b32 v62, v176, v62, v237
	v_bfi_b32 v63, v177, v63, v237
	v_bfi_b32 v64, v178, v64, v237
	v_bfi_b32 v65, v179, v65, v237
	s_waitcnt lgkmcnt(4)
	v_bfe_i32 v176, v175, 0, 1
	v_bfe_i32 v177, v175, 1, 1
	v_bfe_i32 v178, v175, 2, 1
	v_bfe_i32 v179, v175, 3, 1
	v_bfi_b32 v34, v176, v34, v237
	v_bfi_b32 v35, v177, v35, v237
	v_bfi_b32 v36, v178, v36, v237
	v_bfi_b32 v37, v179, v37, v237
	v_bfe_i32 v176, v175, 8, 1
	v_bfe_i32 v177, v175, 9, 1
	v_bfe_i32 v178, v175, 10, 1
	v_bfe_i32 v179, v175, 11, 1
	v_bfi_b32 v38, v176, v38, v237
	v_bfi_b32 v39, v177, v39, v237
	v_bfi_b32 v40, v178, v40, v237
	v_bfi_b32 v41, v179, v41, v237
	v_bfe_i32 v176, v175, 16, 1
	v_bfe_i32 v177, v175, 17, 1
	v_bfe_i32 v178, v175, 18, 1
	v_bfe_i32 v179, v175, 19, 1
	v_bfi_b32 v42, v176, v42, v237
	v_bfi_b32 v43, v177, v43, v237
	v_bfi_b32 v44, v178, v44, v237
	v_bfi_b32 v45, v179, v45, v237
	v_bfe_i32 v176, v175, 24, 1
	v_bfe_i32 v177, v175, 25, 1
	v_bfe_i32 v178, v175, 26, 1
	v_bfe_i32 v179, v175, 27, 1
	v_bfi_b32 v46, v176, v46, v237
	v_bfi_b32 v47, v177, v47, v237
	v_bfi_b32 v48, v178, v48, v237
	v_bfi_b32 v49, v179, v49, v237
	s_nop 1
	s_waitcnt lgkmcnt(3)
	v_mfma_f32_32x32x16_bf16 v[34:49], v[158:161], v[94:97], v[34:49]
	v_mfma_f32_32x32x16_bf16 v[50:65], v[142:145], v[94:97], v[50:65]
	s_waitcnt lgkmcnt(2)
	v_mfma_f32_32x32x16_bf16 v[34:49], v[162:165], v[90:93], v[34:49]
	v_mfma_f32_32x32x16_bf16 v[50:65], v[146:149], v[90:93], v[50:65]
	s_waitcnt lgkmcnt(1)
	v_mfma_f32_32x32x16_bf16 v[34:49], v[166:169], v[86:89], v[34:49]
	v_mfma_f32_32x32x16_bf16 v[50:65], v[150:153], v[86:89], v[50:65]
	s_waitcnt lgkmcnt(0)
	v_mfma_f32_32x32x16_bf16 v[34:49], v[170:173], v[82:85], v[34:49]
	v_mfma_f32_32x32x16_bf16 v[50:65], v[154:157], v[82:85], v[50:65]
	s_nop 11
